# P0 adaLN modulation jobs: silu inputs loaded together; 128 strided weight loads per thread in 4 batches of 32 (two in flight) instead of 16 rounds of 8
# speedup vs baseline: 1.0059x; 1.0059x over previous
.LBB0_77:
	v_add_u32_e32 v84, 0x1000, v1
	global_load_dword v86, v1, s[10:11]
	global_load_dword v87, v1, s[10:11] offset:1024
	global_load_dword v88, v1, s[10:11] offset:2048
	global_load_dword v89, v1, s[10:11] offset:3072
	global_load_dword v90, v1, s[8:9]
	global_load_dword v91, v1, s[8:9] offset:1024
	global_load_dword v92, v1, s[8:9] offset:2048
	global_load_dword v93, v1, s[8:9] offset:3072
	global_load_dword v94, v84, s[8:9]
	global_load_dword v95, v84, s[8:9] offset:1024
	global_load_dword v96, v84, s[8:9] offset:2048
	global_load_dword v97, v84, s[8:9] offset:3072
	s_waitcnt vmcnt(0)
	v_mul_f32_e32 v98, 0xbfb8aa3b, v86
	v_mul_f32_e32 v99, 0xbfb8aa3b, v87
	v_mul_f32_e32 v100, 0xbfb8aa3b, v88
	v_mul_f32_e32 v101, 0xbfb8aa3b, v89
	v_mul_f32_e32 v102, 0xbfb8aa3b, v90
	v_mul_f32_e32 v103, 0xbfb8aa3b, v91
	v_mul_f32_e32 v104, 0xbfb8aa3b, v92
	v_mul_f32_e32 v105, 0xbfb8aa3b, v93
	v_mul_f32_e32 v106, 0xbfb8aa3b, v94
	v_mul_f32_e32 v107, 0xbfb8aa3b, v95
	v_mul_f32_e32 v108, 0xbfb8aa3b, v96
	v_mul_f32_e32 v109, 0xbfb8aa3b, v97
	v_exp_f32_e32 v98, v98
	v_exp_f32_e32 v99, v99
	v_exp_f32_e32 v100, v100
	v_exp_f32_e32 v101, v101
	v_exp_f32_e32 v102, v102
	v_exp_f32_e32 v103, v103
	v_exp_f32_e32 v104, v104
	v_exp_f32_e32 v105, v105
	v_exp_f32_e32 v106, v106
	v_exp_f32_e32 v107, v107
	v_exp_f32_e32 v108, v108
	v_exp_f32_e32 v109, v109
	v_add_f32_e32 v98, 1.0, v98
	v_add_f32_e32 v99, 1.0, v99
	v_add_f32_e32 v100, 1.0, v100
	v_add_f32_e32 v101, 1.0, v101
	v_add_f32_e32 v102, 1.0, v102
	v_add_f32_e32 v103, 1.0, v103
	v_add_f32_e32 v104, 1.0, v104
	v_add_f32_e32 v105, 1.0, v105
	v_add_f32_e32 v106, 1.0, v106
	v_add_f32_e32 v107, 1.0, v107
	v_add_f32_e32 v108, 1.0, v108
	v_add_f32_e32 v109, 1.0, v109
	v_rcp_f32_e32 v98, v98
	v_rcp_f32_e32 v99, v99
	v_rcp_f32_e32 v100, v100
	v_rcp_f32_e32 v101, v101
	v_rcp_f32_e32 v102, v102
	v_rcp_f32_e32 v103, v103
	v_rcp_f32_e32 v104, v104
	v_rcp_f32_e32 v105, v105
	v_rcp_f32_e32 v106, v106
	v_rcp_f32_e32 v107, v107
	v_rcp_f32_e32 v108, v108
	v_rcp_f32_e32 v109, v109
	v_mul_f32_e32 v86, v86, v98
	v_mul_f32_e32 v87, v87, v99
	v_mul_f32_e32 v88, v88, v100
	v_mul_f32_e32 v89, v89, v101
	v_mul_f32_e32 v90, v90, v102
	v_mul_f32_e32 v91, v91, v103
	v_mul_f32_e32 v92, v92, v104
	v_mul_f32_e32 v93, v93, v105
	v_mul_f32_e32 v94, v94, v106
	v_mul_f32_e32 v95, v95, v107
	v_mul_f32_e32 v96, v96, v108
	v_mul_f32_e32 v97, v97, v109
	ds_write_b32 v1, v86
	ds_write_b32 v1, v87 offset:1024
	ds_write_b32 v1, v88 offset:2048
	ds_write_b32 v1, v89 offset:3072
	ds_write_b32 v1, v90 offset:4096
	ds_write_b32 v1, v91 offset:5120
	ds_write_b32 v1, v92 offset:6144
	ds_write_b32 v1, v93 offset:7168
	ds_write_b32 v1, v94 offset:8192
	ds_write_b32 v1, v95 offset:9216
	ds_write_b32 v1, v96 offset:10240
	ds_write_b32 v1, v97 offset:11264
	s_mul_hi_i32 s16, s62, 0x2aaaaaab
	s_lshr_b32 s17, s16, 31
	s_ashr_i32 s18, s16, 4
	s_add_i32 s18, s18, s17
	s_mul_i32 s16, s18, 0x60
	s_sub_i32 s16, s62, s16
	v_lshl_or_b32 v22, s16, 5, v5
	v_ashrrev_i32_e32 v23, 31, v22
	v_lshlrev_b64 v[24:25], 2, v[22:23]
	v_mad_i64_i32 v[24:25], s[16:17], s18, v38, v[24:25]
	v_mov_b32_e32 v2, 0
	v_lshl_add_u64 v[24:25], v[16:17], 0, v[24:25]
	s_mov_b64 s[16:17], 0
	v_mov_b32_e32 v19, v13
	v_mov_b32_e32 v26, 0
	v_mov_b32_e32 v27, v2
	s_waitcnt lgkmcnt(0)
	s_barrier
	s_mov_b32 s16, 0x3000
	s_mov_b32 s17, 0
	v_mov_b32_e32 v42, v24
	v_mov_b32_e32 v43, v25
	global_load_dword v84, v[42:43], off
	v_lshl_add_u64 v[42:43], v[42:43], 0, s[16:17]
	global_load_dword v85, v[42:43], off
	v_lshl_add_u64 v[42:43], v[42:43], 0, s[16:17]
	global_load_dword v86, v[42:43], off
	v_lshl_add_u64 v[42:43], v[42:43], 0, s[16:17]
	global_load_dword v87, v[42:43], off
	v_lshl_add_u64 v[42:43], v[42:43], 0, s[16:17]
	global_load_dword v88, v[42:43], off
	v_lshl_add_u64 v[42:43], v[42:43], 0, s[16:17]
	global_load_dword v89, v[42:43], off
	v_lshl_add_u64 v[42:43], v[42:43], 0, s[16:17]
	global_load_dword v90, v[42:43], off
	v_lshl_add_u64 v[42:43], v[42:43], 0, s[16:17]
	global_load_dword v91, v[42:43], off
	v_lshl_add_u64 v[42:43], v[42:43], 0, s[16:17]
	global_load_dword v92, v[42:43], off
	v_lshl_add_u64 v[42:43], v[42:43], 0, s[16:17]
	global_load_dword v93, v[42:43], off
	v_lshl_add_u64 v[42:43], v[42:43], 0, s[16:17]
	global_load_dword v94, v[42:43], off
	v_lshl_add_u64 v[42:43], v[42:43], 0, s[16:17]
	global_load_dword v95, v[42:43], off
	v_lshl_add_u64 v[42:43], v[42:43], 0, s[16:17]
	global_load_dword v96, v[42:43], off
	v_lshl_add_u64 v[42:43], v[42:43], 0, s[16:17]
	global_load_dword v97, v[42:43], off
	v_lshl_add_u64 v[42:43], v[42:43], 0, s[16:17]
	global_load_dword v98, v[42:43], off
	v_lshl_add_u64 v[42:43], v[42:43], 0, s[16:17]
	global_load_dword v99, v[42:43], off
	v_lshl_add_u64 v[42:43], v[42:43], 0, s[16:17]
	global_load_dword v100, v[42:43], off
	v_lshl_add_u64 v[42:43], v[42:43], 0, s[16:17]
	global_load_dword v101, v[42:43], off
	v_lshl_add_u64 v[42:43], v[42:43], 0, s[16:17]
	global_load_dword v102, v[42:43], off
	v_lshl_add_u64 v[42:43], v[42:43], 0, s[16:17]
	global_load_dword v103, v[42:43], off
	v_lshl_add_u64 v[42:43], v[42:43], 0, s[16:17]
	global_load_dword v104, v[42:43], off
	v_lshl_add_u64 v[42:43], v[42:43], 0, s[16:17]
	global_load_dword v105, v[42:43], off
	v_lshl_add_u64 v[42:43], v[42:43], 0, s[16:17]
	global_load_dword v106, v[42:43], off
	v_lshl_add_u64 v[42:43], v[42:43], 0, s[16:17]
	global_load_dword v107, v[42:43], off
	v_lshl_add_u64 v[42:43], v[42:43], 0, s[16:17]
	global_load_dword v108, v[42:43], off
	v_lshl_add_u64 v[42:43], v[42:43], 0, s[16:17]
	global_load_dword v109, v[42:43], off
	v_lshl_add_u64 v[42:43], v[42:43], 0, s[16:17]
	global_load_dword v110, v[42:43], off
	v_lshl_add_u64 v[42:43], v[42:43], 0, s[16:17]
	global_load_dword v111, v[42:43], off
	v_lshl_add_u64 v[42:43], v[42:43], 0, s[16:17]
	global_load_dword v112, v[42:43], off
	v_lshl_add_u64 v[42:43], v[42:43], 0, s[16:17]
	global_load_dword v113, v[42:43], off
	v_lshl_add_u64 v[42:43], v[42:43], 0, s[16:17]
	global_load_dword v114, v[42:43], off
	v_lshl_add_u64 v[42:43], v[42:43], 0, s[16:17]
	global_load_dword v115, v[42:43], off
	v_lshl_add_u64 v[42:43], v[42:43], 0, s[16:17]
	global_load_dword v116, v[42:43], off
	v_lshl_add_u64 v[42:43], v[42:43], 0, s[16:17]
	global_load_dword v117, v[42:43], off
	v_lshl_add_u64 v[42:43], v[42:43], 0, s[16:17]
	global_load_dword v118, v[42:43], off
	v_lshl_add_u64 v[42:43], v[42:43], 0, s[16:17]
	global_load_dword v119, v[42:43], off
	v_lshl_add_u64 v[42:43], v[42:43], 0, s[16:17]
	global_load_dword v120, v[42:43], off
	v_lshl_add_u64 v[42:43], v[42:43], 0, s[16:17]
	global_load_dword v121, v[42:43], off
	v_lshl_add_u64 v[42:43], v[42:43], 0, s[16:17]
	global_load_dword v122, v[42:43], off
	v_lshl_add_u64 v[42:43], v[42:43], 0, s[16:17]
	global_load_dword v123, v[42:43], off
	v_lshl_add_u64 v[42:43], v[42:43], 0, s[16:17]
	global_load_dword v124, v[42:43], off
	v_lshl_add_u64 v[42:43], v[42:43], 0, s[16:17]
	global_load_dword v125, v[42:43], off
	v_lshl_add_u64 v[42:43], v[42:43], 0, s[16:17]
	global_load_dword v126, v[42:43], off
	v_lshl_add_u64 v[42:43], v[42:43], 0, s[16:17]
	global_load_dword v127, v[42:43], off
	v_lshl_add_u64 v[42:43], v[42:43], 0, s[16:17]
	global_load_dword v128, v[42:43], off
	v_lshl_add_u64 v[42:43], v[42:43], 0, s[16:17]
	global_load_dword v129, v[42:43], off
	v_lshl_add_u64 v[42:43], v[42:43], 0, s[16:17]
	global_load_dword v130, v[42:43], off
	v_lshl_add_u64 v[42:43], v[42:43], 0, s[16:17]
	global_load_dword v131, v[42:43], off
	v_lshl_add_u64 v[42:43], v[42:43], 0, s[16:17]
	global_load_dword v132, v[42:43], off
	v_lshl_add_u64 v[42:43], v[42:43], 0, s[16:17]
	global_load_dword v133, v[42:43], off
	v_lshl_add_u64 v[42:43], v[42:43], 0, s[16:17]
	global_load_dword v134, v[42:43], off
	v_lshl_add_u64 v[42:43], v[42:43], 0, s[16:17]
	global_load_dword v135, v[42:43], off
	v_lshl_add_u64 v[42:43], v[42:43], 0, s[16:17]
	global_load_dword v136, v[42:43], off
	v_lshl_add_u64 v[42:43], v[42:43], 0, s[16:17]
	global_load_dword v137, v[42:43], off
	v_lshl_add_u64 v[42:43], v[42:43], 0, s[16:17]
	global_load_dword v138, v[42:43], off
	v_lshl_add_u64 v[42:43], v[42:43], 0, s[16:17]
	global_load_dword v139, v[42:43], off
	v_lshl_add_u64 v[42:43], v[42:43], 0, s[16:17]
	global_load_dword v140, v[42:43], off
	v_lshl_add_u64 v[42:43], v[42:43], 0, s[16:17]
	global_load_dword v141, v[42:43], off
	v_lshl_add_u64 v[42:43], v[42:43], 0, s[16:17]
	global_load_dword v142, v[42:43], off
	v_lshl_add_u64 v[42:43], v[42:43], 0, s[16:17]
	global_load_dword v143, v[42:43], off
	v_lshl_add_u64 v[42:43], v[42:43], 0, s[16:17]
	global_load_dword v144, v[42:43], off
	v_lshl_add_u64 v[42:43], v[42:43], 0, s[16:17]
	global_load_dword v145, v[42:43], off
	v_lshl_add_u64 v[42:43], v[42:43], 0, s[16:17]
	global_load_dword v146, v[42:43], off
	v_lshl_add_u64 v[42:43], v[42:43], 0, s[16:17]
	global_load_dword v147, v[42:43], off
	v_lshl_add_u64 v[42:43], v[42:43], 0, s[16:17]
	s_waitcnt vmcnt(32)
	ds_read_b128 v[148:151], v19 offset:0
	ds_read_b128 v[152:155], v19 offset:16
	ds_read_b128 v[156:159], v19 offset:32
	ds_read_b128 v[160:163], v19 offset:48
	ds_read_b128 v[180:183], v19 offset:4096
	ds_read_b128 v[184:187], v19 offset:4112
	ds_read_b128 v[188:191], v19 offset:4128
	ds_read_b128 v[192:195], v19 offset:4144
	ds_read_b128 v[196:199], v19 offset:8192
	ds_read_b128 v[200:203], v19 offset:8208
	ds_read_b128 v[204:207], v19 offset:8224
	ds_read_b128 v[208:211], v19 offset:8240
	s_waitcnt lgkmcnt(0)
	v_fmac_f32_e32 v26, v84, v148
	v_fmac_f32_e32 v27, v84, v180
	v_fmac_f32_e32 v2, v84, v196
	v_fmac_f32_e32 v26, v85, v149
	v_fmac_f32_e32 v27, v85, v181
	v_fmac_f32_e32 v2, v85, v197
	v_fmac_f32_e32 v26, v86, v150
	v_fmac_f32_e32 v27, v86, v182
	v_fmac_f32_e32 v2, v86, v198
	v_fmac_f32_e32 v26, v87, v151
	v_fmac_f32_e32 v27, v87, v183
	v_fmac_f32_e32 v2, v87, v199
	v_fmac_f32_e32 v26, v88, v152
	v_fmac_f32_e32 v27, v88, v184
	v_fmac_f32_e32 v2, v88, v200
	v_fmac_f32_e32 v26, v89, v153
	v_fmac_f32_e32 v27, v89, v185
	v_fmac_f32_e32 v2, v89, v201
	v_fmac_f32_e32 v26, v90, v154
	v_fmac_f32_e32 v27, v90, v186
	v_fmac_f32_e32 v2, v90, v202
	v_fmac_f32_e32 v26, v91, v155
	v_fmac_f32_e32 v27, v91, v187
	v_fmac_f32_e32 v2, v91, v203
	v_fmac_f32_e32 v26, v92, v156
	v_fmac_f32_e32 v27, v92, v188
	v_fmac_f32_e32 v2, v92, v204
	v_fmac_f32_e32 v26, v93, v157
	v_fmac_f32_e32 v27, v93, v189
	v_fmac_f32_e32 v2, v93, v205
	v_fmac_f32_e32 v26, v94, v158
	v_fmac_f32_e32 v27, v94, v190
	v_fmac_f32_e32 v2, v94, v206
	v_fmac_f32_e32 v26, v95, v159
	v_fmac_f32_e32 v27, v95, v191
	v_fmac_f32_e32 v2, v95, v207
	v_fmac_f32_e32 v26, v96, v160
	v_fmac_f32_e32 v27, v96, v192
	v_fmac_f32_e32 v2, v96, v208
	v_fmac_f32_e32 v26, v97, v161
	v_fmac_f32_e32 v27, v97, v193
	v_fmac_f32_e32 v2, v97, v209
	v_fmac_f32_e32 v26, v98, v162
	v_fmac_f32_e32 v27, v98, v194
	v_fmac_f32_e32 v2, v98, v210
	v_fmac_f32_e32 v26, v99, v163
	v_fmac_f32_e32 v27, v99, v195
	v_fmac_f32_e32 v2, v99, v211
	ds_read_b128 v[148:151], v19 offset:64
	ds_read_b128 v[152:155], v19 offset:80
	ds_read_b128 v[156:159], v19 offset:96
	ds_read_b128 v[160:163], v19 offset:112
	ds_read_b128 v[180:183], v19 offset:4160
	ds_read_b128 v[184:187], v19 offset:4176
	ds_read_b128 v[188:191], v19 offset:4192
	ds_read_b128 v[192:195], v19 offset:4208
	ds_read_b128 v[196:199], v19 offset:8256
	ds_read_b128 v[200:203], v19 offset:8272
	ds_read_b128 v[204:207], v19 offset:8288
	ds_read_b128 v[208:211], v19 offset:8304
	s_waitcnt lgkmcnt(0)
	v_fmac_f32_e32 v26, v100, v148
	v_fmac_f32_e32 v27, v100, v180
	v_fmac_f32_e32 v2, v100, v196
	v_fmac_f32_e32 v26, v101, v149
	v_fmac_f32_e32 v27, v101, v181
	v_fmac_f32_e32 v2, v101, v197
	v_fmac_f32_e32 v26, v102, v150
	v_fmac_f32_e32 v27, v102, v182
	v_fmac_f32_e32 v2, v102, v198
	v_fmac_f32_e32 v26, v103, v151
	v_fmac_f32_e32 v27, v103, v183
	v_fmac_f32_e32 v2, v103, v199
	v_fmac_f32_e32 v26, v104, v152
	v_fmac_f32_e32 v27, v104, v184
	v_fmac_f32_e32 v2, v104, v200
	v_fmac_f32_e32 v26, v105, v153
	v_fmac_f32_e32 v27, v105, v185
	v_fmac_f32_e32 v2, v105, v201
	v_fmac_f32_e32 v26, v106, v154
	v_fmac_f32_e32 v27, v106, v186
	v_fmac_f32_e32 v2, v106, v202
	v_fmac_f32_e32 v26, v107, v155
	v_fmac_f32_e32 v27, v107, v187
	v_fmac_f32_e32 v2, v107, v203
	v_fmac_f32_e32 v26, v108, v156
	v_fmac_f32_e32 v27, v108, v188
	v_fmac_f32_e32 v2, v108, v204
	v_fmac_f32_e32 v26, v109, v157
	v_fmac_f32_e32 v27, v109, v189
	v_fmac_f32_e32 v2, v109, v205
	v_fmac_f32_e32 v26, v110, v158
	v_fmac_f32_e32 v27, v110, v190
	v_fmac_f32_e32 v2, v110, v206
	v_fmac_f32_e32 v26, v111, v159
	v_fmac_f32_e32 v27, v111, v191
	v_fmac_f32_e32 v2, v111, v207
	v_fmac_f32_e32 v26, v112, v160
	v_fmac_f32_e32 v27, v112, v192
	v_fmac_f32_e32 v2, v112, v208
	v_fmac_f32_e32 v26, v113, v161
	v_fmac_f32_e32 v27, v113, v193
	v_fmac_f32_e32 v2, v113, v209
	v_fmac_f32_e32 v26, v114, v162
	v_fmac_f32_e32 v27, v114, v194
	v_fmac_f32_e32 v2, v114, v210
	v_fmac_f32_e32 v26, v115, v163
	v_fmac_f32_e32 v27, v115, v195
	v_fmac_f32_e32 v2, v115, v211
	global_load_dword v84, v[42:43], off
	v_lshl_add_u64 v[42:43], v[42:43], 0, s[16:17]
	global_load_dword v85, v[42:43], off
	v_lshl_add_u64 v[42:43], v[42:43], 0, s[16:17]
	global_load_dword v86, v[42:43], off
	v_lshl_add_u64 v[42:43], v[42:43], 0, s[16:17]
	global_load_dword v87, v[42:43], off
	v_lshl_add_u64 v[42:43], v[42:43], 0, s[16:17]
	global_load_dword v88, v[42:43], off
	v_lshl_add_u64 v[42:43], v[42:43], 0, s[16:17]
	global_load_dword v89, v[42:43], off
	v_lshl_add_u64 v[42:43], v[42:43], 0, s[16:17]
	global_load_dword v90, v[42:43], off
	v_lshl_add_u64 v[42:43], v[42:43], 0, s[16:17]
	global_load_dword v91, v[42:43], off
	v_lshl_add_u64 v[42:43], v[42:43], 0, s[16:17]
	global_load_dword v92, v[42:43], off
	v_lshl_add_u64 v[42:43], v[42:43], 0, s[16:17]
	global_load_dword v93, v[42:43], off
	v_lshl_add_u64 v[42:43], v[42:43], 0, s[16:17]
	global_load_dword v94, v[42:43], off
	v_lshl_add_u64 v[42:43], v[42:43], 0, s[16:17]
	global_load_dword v95, v[42:43], off
	v_lshl_add_u64 v[42:43], v[42:43], 0, s[16:17]
	global_load_dword v96, v[42:43], off
	v_lshl_add_u64 v[42:43], v[42:43], 0, s[16:17]
	global_load_dword v97, v[42:43], off
	v_lshl_add_u64 v[42:43], v[42:43], 0, s[16:17]
	global_load_dword v98, v[42:43], off
	v_lshl_add_u64 v[42:43], v[42:43], 0, s[16:17]
	global_load_dword v99, v[42:43], off
	v_lshl_add_u64 v[42:43], v[42:43], 0, s[16:17]
	global_load_dword v100, v[42:43], off
	v_lshl_add_u64 v[42:43], v[42:43], 0, s[16:17]
	global_load_dword v101, v[42:43], off
	v_lshl_add_u64 v[42:43], v[42:43], 0, s[16:17]
	global_load_dword v102, v[42:43], off
	v_lshl_add_u64 v[42:43], v[42:43], 0, s[16:17]
	global_load_dword v103, v[42:43], off
	v_lshl_add_u64 v[42:43], v[42:43], 0, s[16:17]
	global_load_dword v104, v[42:43], off
	v_lshl_add_u64 v[42:43], v[42:43], 0, s[16:17]
	global_load_dword v105, v[42:43], off
	v_lshl_add_u64 v[42:43], v[42:43], 0, s[16:17]
	global_load_dword v106, v[42:43], off
	v_lshl_add_u64 v[42:43], v[42:43], 0, s[16:17]
	global_load_dword v107, v[42:43], off
	v_lshl_add_u64 v[42:43], v[42:43], 0, s[16:17]
	global_load_dword v108, v[42:43], off
	v_lshl_add_u64 v[42:43], v[42:43], 0, s[16:17]
	global_load_dword v109, v[42:43], off
	v_lshl_add_u64 v[42:43], v[42:43], 0, s[16:17]
	global_load_dword v110, v[42:43], off
	v_lshl_add_u64 v[42:43], v[42:43], 0, s[16:17]
	global_load_dword v111, v[42:43], off
	v_lshl_add_u64 v[42:43], v[42:43], 0, s[16:17]
	global_load_dword v112, v[42:43], off
	v_lshl_add_u64 v[42:43], v[42:43], 0, s[16:17]
	global_load_dword v113, v[42:43], off
	v_lshl_add_u64 v[42:43], v[42:43], 0, s[16:17]
	global_load_dword v114, v[42:43], off
	v_lshl_add_u64 v[42:43], v[42:43], 0, s[16:17]
	global_load_dword v115, v[42:43], off
	v_lshl_add_u64 v[42:43], v[42:43], 0, s[16:17]
	s_waitcnt vmcnt(32)
	ds_read_b128 v[148:151], v19 offset:128
	ds_read_b128 v[152:155], v19 offset:144
	ds_read_b128 v[156:159], v19 offset:160
	ds_read_b128 v[160:163], v19 offset:176
	ds_read_b128 v[180:183], v19 offset:4224
	ds_read_b128 v[184:187], v19 offset:4240
	ds_read_b128 v[188:191], v19 offset:4256
	ds_read_b128 v[192:195], v19 offset:4272
	ds_read_b128 v[196:199], v19 offset:8320
	ds_read_b128 v[200:203], v19 offset:8336
	ds_read_b128 v[204:207], v19 offset:8352
	ds_read_b128 v[208:211], v19 offset:8368
	s_waitcnt lgkmcnt(0)
	v_fmac_f32_e32 v26, v116, v148
	v_fmac_f32_e32 v27, v116, v180
	v_fmac_f32_e32 v2, v116, v196
	v_fmac_f32_e32 v26, v117, v149
	v_fmac_f32_e32 v27, v117, v181
	v_fmac_f32_e32 v2, v117, v197
	v_fmac_f32_e32 v26, v118, v150
	v_fmac_f32_e32 v27, v118, v182
	v_fmac_f32_e32 v2, v118, v198
	v_fmac_f32_e32 v26, v119, v151
	v_fmac_f32_e32 v27, v119, v183
	v_fmac_f32_e32 v2, v119, v199
	v_fmac_f32_e32 v26, v120, v152
	v_fmac_f32_e32 v27, v120, v184
	v_fmac_f32_e32 v2, v120, v200
	v_fmac_f32_e32 v26, v121, v153
	v_fmac_f32_e32 v27, v121, v185
	v_fmac_f32_e32 v2, v121, v201
	v_fmac_f32_e32 v26, v122, v154
	v_fmac_f32_e32 v27, v122, v186
	v_fmac_f32_e32 v2, v122, v202
	v_fmac_f32_e32 v26, v123, v155
	v_fmac_f32_e32 v27, v123, v187
	v_fmac_f32_e32 v2, v123, v203
	v_fmac_f32_e32 v26, v124, v156
	v_fmac_f32_e32 v27, v124, v188
	v_fmac_f32_e32 v2, v124, v204
	v_fmac_f32_e32 v26, v125, v157
	v_fmac_f32_e32 v27, v125, v189
	v_fmac_f32_e32 v2, v125, v205
	v_fmac_f32_e32 v26, v126, v158
	v_fmac_f32_e32 v27, v126, v190
	v_fmac_f32_e32 v2, v126, v206
	v_fmac_f32_e32 v26, v127, v159
	v_fmac_f32_e32 v27, v127, v191
	v_fmac_f32_e32 v2, v127, v207
	v_fmac_f32_e32 v26, v128, v160
	v_fmac_f32_e32 v27, v128, v192
	v_fmac_f32_e32 v2, v128, v208
	v_fmac_f32_e32 v26, v129, v161
	v_fmac_f32_e32 v27, v129, v193
	v_fmac_f32_e32 v2, v129, v209
	v_fmac_f32_e32 v26, v130, v162
	v_fmac_f32_e32 v27, v130, v194
	v_fmac_f32_e32 v2, v130, v210
	v_fmac_f32_e32 v26, v131, v163
	v_fmac_f32_e32 v27, v131, v195
	v_fmac_f32_e32 v2, v131, v211
	ds_read_b128 v[148:151], v19 offset:192
	ds_read_b128 v[152:155], v19 offset:208
	ds_read_b128 v[156:159], v19 offset:224
	ds_read_b128 v[160:163], v19 offset:240
	ds_read_b128 v[180:183], v19 offset:4288
	ds_read_b128 v[184:187], v19 offset:4304
	ds_read_b128 v[188:191], v19 offset:4320
	ds_read_b128 v[192:195], v19 offset:4336
	ds_read_b128 v[196:199], v19 offset:8384
	ds_read_b128 v[200:203], v19 offset:8400
	ds_read_b128 v[204:207], v19 offset:8416
	ds_read_b128 v[208:211], v19 offset:8432
	s_waitcnt lgkmcnt(0)
	v_fmac_f32_e32 v26, v132, v148
	v_fmac_f32_e32 v27, v132, v180
	v_fmac_f32_e32 v2, v132, v196
	v_fmac_f32_e32 v26, v133, v149
	v_fmac_f32_e32 v27, v133, v181
	v_fmac_f32_e32 v2, v133, v197
	v_fmac_f32_e32 v26, v134, v150
	v_fmac_f32_e32 v27, v134, v182
	v_fmac_f32_e32 v2, v134, v198
	v_fmac_f32_e32 v26, v135, v151
	v_fmac_f32_e32 v27, v135, v183
	v_fmac_f32_e32 v2, v135, v199
	v_fmac_f32_e32 v26, v136, v152
	v_fmac_f32_e32 v27, v136, v184
	v_fmac_f32_e32 v2, v136, v200
	v_fmac_f32_e32 v26, v137, v153
	v_fmac_f32_e32 v27, v137, v185
	v_fmac_f32_e32 v2, v137, v201
	v_fmac_f32_e32 v26, v138, v154
	v_fmac_f32_e32 v27, v138, v186
	v_fmac_f32_e32 v2, v138, v202
	v_fmac_f32_e32 v26, v139, v155
	v_fmac_f32_e32 v27, v139, v187
	v_fmac_f32_e32 v2, v139, v203
	v_fmac_f32_e32 v26, v140, v156
	v_fmac_f32_e32 v27, v140, v188
	v_fmac_f32_e32 v2, v140, v204
	v_fmac_f32_e32 v26, v141, v157
	v_fmac_f32_e32 v27, v141, v189
	v_fmac_f32_e32 v2, v141, v205
	v_fmac_f32_e32 v26, v142, v158
	v_fmac_f32_e32 v27, v142, v190
	v_fmac_f32_e32 v2, v142, v206
	v_fmac_f32_e32 v26, v143, v159
	v_fmac_f32_e32 v27, v143, v191
	v_fmac_f32_e32 v2, v143, v207
	v_fmac_f32_e32 v26, v144, v160
	v_fmac_f32_e32 v27, v144, v192
	v_fmac_f32_e32 v2, v144, v208
	v_fmac_f32_e32 v26, v145, v161
	v_fmac_f32_e32 v27, v145, v193
	v_fmac_f32_e32 v2, v145, v209
	v_fmac_f32_e32 v26, v146, v162
	v_fmac_f32_e32 v27, v146, v194
	v_fmac_f32_e32 v2, v146, v210
	v_fmac_f32_e32 v26, v147, v163
	v_fmac_f32_e32 v27, v147, v195
	v_fmac_f32_e32 v2, v147, v211
	global_load_dword v116, v[42:43], off
	v_lshl_add_u64 v[42:43], v[42:43], 0, s[16:17]
	global_load_dword v117, v[42:43], off
	v_lshl_add_u64 v[42:43], v[42:43], 0, s[16:17]
	global_load_dword v118, v[42:43], off
	v_lshl_add_u64 v[42:43], v[42:43], 0, s[16:17]
	global_load_dword v119, v[42:43], off
	v_lshl_add_u64 v[42:43], v[42:43], 0, s[16:17]
	global_load_dword v120, v[42:43], off
	v_lshl_add_u64 v[42:43], v[42:43], 0, s[16:17]
	global_load_dword v121, v[42:43], off
	v_lshl_add_u64 v[42:43], v[42:43], 0, s[16:17]
	global_load_dword v122, v[42:43], off
	v_lshl_add_u64 v[42:43], v[42:43], 0, s[16:17]
	global_load_dword v123, v[42:43], off
	v_lshl_add_u64 v[42:43], v[42:43], 0, s[16:17]
	global_load_dword v124, v[42:43], off
	v_lshl_add_u64 v[42:43], v[42:43], 0, s[16:17]
	global_load_dword v125, v[42:43], off
	v_lshl_add_u64 v[42:43], v[42:43], 0, s[16:17]
	global_load_dword v126, v[42:43], off
	v_lshl_add_u64 v[42:43], v[42:43], 0, s[16:17]
	global_load_dword v127, v[42:43], off
	v_lshl_add_u64 v[42:43], v[42:43], 0, s[16:17]
	global_load_dword v128, v[42:43], off
	v_lshl_add_u64 v[42:43], v[42:43], 0, s[16:17]
	global_load_dword v129, v[42:43], off
	v_lshl_add_u64 v[42:43], v[42:43], 0, s[16:17]
	global_load_dword v130, v[42:43], off
	v_lshl_add_u64 v[42:43], v[42:43], 0, s[16:17]
	global_load_dword v131, v[42:43], off
	v_lshl_add_u64 v[42:43], v[42:43], 0, s[16:17]
	global_load_dword v132, v[42:43], off
	v_lshl_add_u64 v[42:43], v[42:43], 0, s[16:17]
	global_load_dword v133, v[42:43], off
	v_lshl_add_u64 v[42:43], v[42:43], 0, s[16:17]
	global_load_dword v134, v[42:43], off
	v_lshl_add_u64 v[42:43], v[42:43], 0, s[16:17]
	global_load_dword v135, v[42:43], off
	v_lshl_add_u64 v[42:43], v[42:43], 0, s[16:17]
	global_load_dword v136, v[42:43], off
	v_lshl_add_u64 v[42:43], v[42:43], 0, s[16:17]
	global_load_dword v137, v[42:43], off
	v_lshl_add_u64 v[42:43], v[42:43], 0, s[16:17]
	global_load_dword v138, v[42:43], off
	v_lshl_add_u64 v[42:43], v[42:43], 0, s[16:17]
	global_load_dword v139, v[42:43], off
	v_lshl_add_u64 v[42:43], v[42:43], 0, s[16:17]
	global_load_dword v140, v[42:43], off
	v_lshl_add_u64 v[42:43], v[42:43], 0, s[16:17]
	global_load_dword v141, v[42:43], off
	v_lshl_add_u64 v[42:43], v[42:43], 0, s[16:17]
	global_load_dword v142, v[42:43], off
	v_lshl_add_u64 v[42:43], v[42:43], 0, s[16:17]
	global_load_dword v143, v[42:43], off
	v_lshl_add_u64 v[42:43], v[42:43], 0, s[16:17]
	global_load_dword v144, v[42:43], off
	v_lshl_add_u64 v[42:43], v[42:43], 0, s[16:17]
	global_load_dword v145, v[42:43], off
	v_lshl_add_u64 v[42:43], v[42:43], 0, s[16:17]
	global_load_dword v146, v[42:43], off
	v_lshl_add_u64 v[42:43], v[42:43], 0, s[16:17]
	global_load_dword v147, v[42:43], off
	v_lshl_add_u64 v[42:43], v[42:43], 0, s[16:17]
	s_waitcnt vmcnt(32)
	ds_read_b128 v[148:151], v19 offset:256
	ds_read_b128 v[152:155], v19 offset:272
	ds_read_b128 v[156:159], v19 offset:288
	ds_read_b128 v[160:163], v19 offset:304
	ds_read_b128 v[180:183], v19 offset:4352
	ds_read_b128 v[184:187], v19 offset:4368
	ds_read_b128 v[188:191], v19 offset:4384
	ds_read_b128 v[192:195], v19 offset:4400
	ds_read_b128 v[196:199], v19 offset:8448
	ds_read_b128 v[200:203], v19 offset:8464
	ds_read_b128 v[204:207], v19 offset:8480
	ds_read_b128 v[208:211], v19 offset:8496
	s_waitcnt lgkmcnt(0)
	v_fmac_f32_e32 v26, v84, v148
	v_fmac_f32_e32 v27, v84, v180
	v_fmac_f32_e32 v2, v84, v196
	v_fmac_f32_e32 v26, v85, v149
	v_fmac_f32_e32 v27, v85, v181
	v_fmac_f32_e32 v2, v85, v197
	v_fmac_f32_e32 v26, v86, v150
	v_fmac_f32_e32 v27, v86, v182
	v_fmac_f32_e32 v2, v86, v198
	v_fmac_f32_e32 v26, v87, v151
	v_fmac_f32_e32 v27, v87, v183
	v_fmac_f32_e32 v2, v87, v199
	v_fmac_f32_e32 v26, v88, v152
	v_fmac_f32_e32 v27, v88, v184
	v_fmac_f32_e32 v2, v88, v200
	v_fmac_f32_e32 v26, v89, v153
	v_fmac_f32_e32 v27, v89, v185
	v_fmac_f32_e32 v2, v89, v201
	v_fmac_f32_e32 v26, v90, v154
	v_fmac_f32_e32 v27, v90, v186
	v_fmac_f32_e32 v2, v90, v202
	v_fmac_f32_e32 v26, v91, v155
	v_fmac_f32_e32 v27, v91, v187
	v_fmac_f32_e32 v2, v91, v203
	v_fmac_f32_e32 v26, v92, v156
	v_fmac_f32_e32 v27, v92, v188
	v_fmac_f32_e32 v2, v92, v204
	v_fmac_f32_e32 v26, v93, v157
	v_fmac_f32_e32 v27, v93, v189
	v_fmac_f32_e32 v2, v93, v205
	v_fmac_f32_e32 v26, v94, v158
	v_fmac_f32_e32 v27, v94, v190
	v_fmac_f32_e32 v2, v94, v206
	v_fmac_f32_e32 v26, v95, v159
	v_fmac_f32_e32 v27, v95, v191
	v_fmac_f32_e32 v2, v95, v207
	v_fmac_f32_e32 v26, v96, v160
	v_fmac_f32_e32 v27, v96, v192
	v_fmac_f32_e32 v2, v96, v208
	v_fmac_f32_e32 v26, v97, v161
	v_fmac_f32_e32 v27, v97, v193
	v_fmac_f32_e32 v2, v97, v209
	v_fmac_f32_e32 v26, v98, v162
	v_fmac_f32_e32 v27, v98, v194
	v_fmac_f32_e32 v2, v98, v210
	v_fmac_f32_e32 v26, v99, v163
	v_fmac_f32_e32 v27, v99, v195
	v_fmac_f32_e32 v2, v99, v211
	ds_read_b128 v[148:151], v19 offset:320
	ds_read_b128 v[152:155], v19 offset:336
	ds_read_b128 v[156:159], v19 offset:352
	ds_read_b128 v[160:163], v19 offset:368
	ds_read_b128 v[180:183], v19 offset:4416
	ds_read_b128 v[184:187], v19 offset:4432
	ds_read_b128 v[188:191], v19 offset:4448
	ds_read_b128 v[192:195], v19 offset:4464
	ds_read_b128 v[196:199], v19 offset:8512
	ds_read_b128 v[200:203], v19 offset:8528
	ds_read_b128 v[204:207], v19 offset:8544
	ds_read_b128 v[208:211], v19 offset:8560
	s_waitcnt lgkmcnt(0)
	v_fmac_f32_e32 v26, v100, v148
	v_fmac_f32_e32 v27, v100, v180
	v_fmac_f32_e32 v2, v100, v196
	v_fmac_f32_e32 v26, v101, v149
	v_fmac_f32_e32 v27, v101, v181
	v_fmac_f32_e32 v2, v101, v197
	v_fmac_f32_e32 v26, v102, v150
	v_fmac_f32_e32 v27, v102, v182
	v_fmac_f32_e32 v2, v102, v198
	v_fmac_f32_e32 v26, v103, v151
	v_fmac_f32_e32 v27, v103, v183
	v_fmac_f32_e32 v2, v103, v199
	v_fmac_f32_e32 v26, v104, v152
	v_fmac_f32_e32 v27, v104, v184
	v_fmac_f32_e32 v2, v104, v200
	v_fmac_f32_e32 v26, v105, v153
	v_fmac_f32_e32 v27, v105, v185
	v_fmac_f32_e32 v2, v105, v201
	v_fmac_f32_e32 v26, v106, v154
	v_fmac_f32_e32 v27, v106, v186
	v_fmac_f32_e32 v2, v106, v202
	v_fmac_f32_e32 v26, v107, v155
	v_fmac_f32_e32 v27, v107, v187
	v_fmac_f32_e32 v2, v107, v203
	v_fmac_f32_e32 v26, v108, v156
	v_fmac_f32_e32 v27, v108, v188
	v_fmac_f32_e32 v2, v108, v204
	v_fmac_f32_e32 v26, v109, v157
	v_fmac_f32_e32 v27, v109, v189
	v_fmac_f32_e32 v2, v109, v205
	v_fmac_f32_e32 v26, v110, v158
	v_fmac_f32_e32 v27, v110, v190
	v_fmac_f32_e32 v2, v110, v206
	v_fmac_f32_e32 v26, v111, v159
	v_fmac_f32_e32 v27, v111, v191
	v_fmac_f32_e32 v2, v111, v207
	v_fmac_f32_e32 v26, v112, v160
	v_fmac_f32_e32 v27, v112, v192
	v_fmac_f32_e32 v2, v112, v208
	v_fmac_f32_e32 v26, v113, v161
	v_fmac_f32_e32 v27, v113, v193
	v_fmac_f32_e32 v2, v113, v209
	v_fmac_f32_e32 v26, v114, v162
	v_fmac_f32_e32 v27, v114, v194
	v_fmac_f32_e32 v2, v114, v210
	v_fmac_f32_e32 v26, v115, v163
	v_fmac_f32_e32 v27, v115, v195
	v_fmac_f32_e32 v2, v115, v211
	s_waitcnt vmcnt(0)
	ds_read_b128 v[148:151], v19 offset:384
	ds_read_b128 v[152:155], v19 offset:400
	ds_read_b128 v[156:159], v19 offset:416
	ds_read_b128 v[160:163], v19 offset:432
	ds_read_b128 v[180:183], v19 offset:4480
	ds_read_b128 v[184:187], v19 offset:4496
	ds_read_b128 v[188:191], v19 offset:4512
	ds_read_b128 v[192:195], v19 offset:4528
	ds_read_b128 v[196:199], v19 offset:8576
	ds_read_b128 v[200:203], v19 offset:8592
	ds_read_b128 v[204:207], v19 offset:8608
	ds_read_b128 v[208:211], v19 offset:8624
	s_waitcnt lgkmcnt(0)
	v_fmac_f32_e32 v26, v116, v148
	v_fmac_f32_e32 v27, v116, v180
	v_fmac_f32_e32 v2, v116, v196
	v_fmac_f32_e32 v26, v117, v149
	v_fmac_f32_e32 v27, v117, v181
	v_fmac_f32_e32 v2, v117, v197
	v_fmac_f32_e32 v26, v118, v150
	v_fmac_f32_e32 v27, v118, v182
	v_fmac_f32_e32 v2, v118, v198
	v_fmac_f32_e32 v26, v119, v151
	v_fmac_f32_e32 v27, v119, v183
	v_fmac_f32_e32 v2, v119, v199
	v_fmac_f32_e32 v26, v120, v152
	v_fmac_f32_e32 v27, v120, v184
	v_fmac_f32_e32 v2, v120, v200
	v_fmac_f32_e32 v26, v121, v153
	v_fmac_f32_e32 v27, v121, v185
	v_fmac_f32_e32 v2, v121, v201
	v_fmac_f32_e32 v26, v122, v154
	v_fmac_f32_e32 v27, v122, v186
	v_fmac_f32_e32 v2, v122, v202
	v_fmac_f32_e32 v26, v123, v155
	v_fmac_f32_e32 v27, v123, v187
	v_fmac_f32_e32 v2, v123, v203
	v_fmac_f32_e32 v26, v124, v156
	v_fmac_f32_e32 v27, v124, v188
	v_fmac_f32_e32 v2, v124, v204
	v_fmac_f32_e32 v26, v125, v157
	v_fmac_f32_e32 v27, v125, v189
	v_fmac_f32_e32 v2, v125, v205
	v_fmac_f32_e32 v26, v126, v158
	v_fmac_f32_e32 v27, v126, v190
	v_fmac_f32_e32 v2, v126, v206
	v_fmac_f32_e32 v26, v127, v159
	v_fmac_f32_e32 v27, v127, v191
	v_fmac_f32_e32 v2, v127, v207
	v_fmac_f32_e32 v26, v128, v160
	v_fmac_f32_e32 v27, v128, v192
	v_fmac_f32_e32 v2, v128, v208
	v_fmac_f32_e32 v26, v129, v161
	v_fmac_f32_e32 v27, v129, v193
	v_fmac_f32_e32 v2, v129, v209
	v_fmac_f32_e32 v26, v130, v162
	v_fmac_f32_e32 v27, v130, v194
	v_fmac_f32_e32 v2, v130, v210
	v_fmac_f32_e32 v26, v131, v163
	v_fmac_f32_e32 v27, v131, v195
	v_fmac_f32_e32 v2, v131, v211
	ds_read_b128 v[148:151], v19 offset:448
	ds_read_b128 v[152:155], v19 offset:464
	ds_read_b128 v[156:159], v19 offset:480
	ds_read_b128 v[160:163], v19 offset:496
	ds_read_b128 v[180:183], v19 offset:4544
	ds_read_b128 v[184:187], v19 offset:4560
	ds_read_b128 v[188:191], v19 offset:4576
	ds_read_b128 v[192:195], v19 offset:4592
	ds_read_b128 v[196:199], v19 offset:8640
	ds_read_b128 v[200:203], v19 offset:8656
	ds_read_b128 v[204:207], v19 offset:8672
	ds_read_b128 v[208:211], v19 offset:8688
	s_waitcnt lgkmcnt(0)
	v_fmac_f32_e32 v26, v132, v148
	v_fmac_f32_e32 v27, v132, v180
	v_fmac_f32_e32 v2, v132, v196
	v_fmac_f32_e32 v26, v133, v149
	v_fmac_f32_e32 v27, v133, v181
	v_fmac_f32_e32 v2, v133, v197
	v_fmac_f32_e32 v26, v134, v150
	v_fmac_f32_e32 v27, v134, v182
	v_fmac_f32_e32 v2, v134, v198
	v_fmac_f32_e32 v26, v135, v151
	v_fmac_f32_e32 v27, v135, v183
	v_fmac_f32_e32 v2, v135, v199
	v_fmac_f32_e32 v26, v136, v152
	v_fmac_f32_e32 v27, v136, v184
	v_fmac_f32_e32 v2, v136, v200
	v_fmac_f32_e32 v26, v137, v153
	v_fmac_f32_e32 v27, v137, v185
	v_fmac_f32_e32 v2, v137, v201
	v_fmac_f32_e32 v26, v138, v154
	v_fmac_f32_e32 v27, v138, v186
	v_fmac_f32_e32 v2, v138, v202
	v_fmac_f32_e32 v26, v139, v155
	v_fmac_f32_e32 v27, v139, v187
	v_fmac_f32_e32 v2, v139, v203
	v_fmac_f32_e32 v26, v140, v156
	v_fmac_f32_e32 v27, v140, v188
	v_fmac_f32_e32 v2, v140, v204
	v_fmac_f32_e32 v26, v141, v157
	v_fmac_f32_e32 v27, v141, v189
	v_fmac_f32_e32 v2, v141, v205
	v_fmac_f32_e32 v26, v142, v158
	v_fmac_f32_e32 v27, v142, v190
	v_fmac_f32_e32 v2, v142, v206
	v_fmac_f32_e32 v26, v143, v159
	v_fmac_f32_e32 v27, v143, v191
	v_fmac_f32_e32 v2, v143, v207
	v_fmac_f32_e32 v26, v144, v160
	v_fmac_f32_e32 v27, v144, v192
	v_fmac_f32_e32 v2, v144, v208
	v_fmac_f32_e32 v26, v145, v161
	v_fmac_f32_e32 v27, v145, v193
	v_fmac_f32_e32 v2, v145, v209
	v_fmac_f32_e32 v26, v146, v162
	v_fmac_f32_e32 v27, v146, v194
	v_fmac_f32_e32 v2, v146, v210
	v_fmac_f32_e32 v26, v147, v163
	v_fmac_f32_e32 v27, v147, v195
	v_fmac_f32_e32 v2, v147, v211
	ds_write2_b32 v33, v26, v27 offset1:1
	ds_write_b32 v7, v2 offset:12296
	s_waitcnt lgkmcnt(0)
	s_barrier
	s_and_saveexec_b64 s[16:17], s[6:7]
	s_cbranch_execz .LBB0_22
	s_mul_i32 s19, s18, 0xc00
	v_add_u32_e32 v24, s19, v22
	v_ashrrev_i32_e32 v25, 31, v24
	v_lshl_add_u64 v[24:25], v[24:25], 2, s[14:15]
	global_load_dword v2, v[24:25], off
	ds_read2_b32 v[24:25], v39 offset1:96
	ds_read2st64_b32 v[26:27], v34 offset0:51 offset1:54
	ds_read2_b32 v[42:43], v40 offset0:96 offset1:192
	ds_read_b32 v19, v35 offset:12288
	ds_read_b32 v21, v36 offset:12288
	s_waitcnt lgkmcnt(4)
	v_add_f32_e32 v24, 0, v24
	v_add_f32_e32 v24, v24, v25
	s_waitcnt lgkmcnt(3)
	v_add_f32_e32 v24, v24, v26
	s_waitcnt lgkmcnt(1)
	v_add_f32_e32 v19, v24, v19
	v_add_f32_e32 v19, v19, v27
	v_mad_u64_u32 v[44:45], s[18:19], s18, 3, v[6:7]
	v_add_f32_e32 v19, v19, v42
	v_mad_u64_u32 v[22:23], s[18:19], v44, s52, v[22:23]
	v_add_f32_e32 v19, v19, v43
	v_ashrrev_i32_e32 v23, 31, v22
	s_waitcnt lgkmcnt(0)
	v_add_f32_e32 v19, v19, v21
	v_lshl_add_u64 v[22:23], v[22:23], 2, s[12:13]
	s_waitcnt vmcnt(0)
	v_add_f32_e32 v2, v19, v2
	global_store_dword v[22:23], v2, off
	s_branch .LBB0_22
